# counted lgkmcnt waits for the K-fragment reads of the neighbourhood-attention QK MFMAs
# speedup vs baseline: 1.0027x; 1.0027x over previous
.LBB0_510:
	s_lshl_b32 s72, s70, 14
	s_add_i32 s72, s72, 0
	v_add_u32_e32 v1, s72, v90
	v_add_u32_e32 v2, s72, v91
	ds_read_b128 v[28:31], v1
	ds_read_b128 v[32:35], v1 offset:2048
	ds_read_b128 v[36:39], v2
	ds_read_b128 v[40:43], v2 offset:2048
	ds_read_b128 v[44:47], v1 offset:4096
	ds_read_b128 v[48:51], v1 offset:6144
	ds_read_b128 v[52:55], v2 offset:4096
	ds_read_b128 v[56:59], v2 offset:6144
	s_waitcnt lgkmcnt(7)
	v_mfma_f32_16x16x32_bf16 v[28:31], v[28:31], v[4:7], 0
	v_add_u32_e32 v1, s72, v92
	v_add_u32_e32 v2, s72, v93
	s_waitcnt lgkmcnt(5)
	v_mfma_f32_16x16x32_bf16 v[74:77], v[36:39], v[8:11], v[28:31]
	v_mfma_f32_16x16x32_bf16 v[28:31], v[32:35], v[4:7], 0
	s_waitcnt lgkmcnt(4)
	v_mfma_f32_16x16x32_bf16 v[68:71], v[40:43], v[8:11], v[28:31]
	s_waitcnt lgkmcnt(3)
	v_mfma_f32_16x16x32_bf16 v[28:31], v[44:47], v[4:7], 0
	s_waitcnt lgkmcnt(1)
	v_mfma_f32_16x16x32_bf16 v[64:67], v[52:55], v[8:11], v[28:31]
	v_mfma_f32_16x16x32_bf16 v[28:31], v[48:51], v[4:7], 0
	s_waitcnt lgkmcnt(0)
	v_mfma_f32_16x16x32_bf16 v[60:63], v[56:59], v[8:11], v[28:31]
	ds_read_b64 v[52:53], v1 offset:10240
	ds_read_b64 v[54:55], v2 offset:10240
	ds_read_b64 v[140:141], v1 offset:8192
	ds_read_b64 v[142:143], v2 offset:8192
	ds_read_b64 v[56:57], v1 offset:12288
	ds_read_b64 v[58:59], v2 offset:12288
	ds_read_b64 v[44:45], v1 offset:14336
	ds_read_b64 v[46:47], v2 offset:14336
	v_add_u32_e32 v1, s72, v96
	v_add_u32_e32 v2, s72, v97
	ds_read_b64 v[32:33], v1 offset:8192
	ds_read_b64 v[34:35], v2 offset:8192
	ds_read_b64 v[36:37], v1 offset:10240
	ds_read_b64 v[38:39], v2 offset:10240
	ds_read_b64 v[40:41], v1 offset:12288
	ds_read_b64 v[42:43], v2 offset:12288
	ds_read_b64 v[28:29], v1 offset:14336
	ds_read_b64 v[30:31], v2 offset:14336
	s_cmp_gt_u32 s71, 7
	s_mov_b32 s71, 0x3e38aa3b
	s_cbranch_scc1 .LBB0_544
	v_add_u32_e32 v1, s69, v98
	v_add_u32_e32 v1, 0x103a0, v1
	ds_read_b32 v102, v1
	ds_read_b32 v103, v1 offset:4
	ds_read_b32 v104, v1 offset:8
	ds_read_b32 v105, v1 offset:12
	ds_read_b32 v106, v1 offset:64
	ds_read_b32 v107, v1 offset:68
	ds_read_b32 v108, v1 offset:72
	ds_read_b32 v109, v1 offset:76
	ds_read_b32 v110, v1 offset:128
	ds_read_b32 v111, v1 offset:132
	ds_read_b32 v112, v1 offset:136
	ds_read_b32 v113, v1 offset:140
	ds_read_b32 v114, v1 offset:192
	ds_read_b32 v115, v1 offset:196
	ds_read_b32 v210, v1 offset:200
	ds_read_b32 v211, v1 offset:204
	v_mov_b32_e32 v2, 0xff800000
	s_mov_b32 s71, 1.0
	s_waitcnt lgkmcnt(15)
	v_mul_f32_e32 v3, s5, v102
	v_mul_f32_e32 v74, s4, v74
	v_add_f32_e32 v74, v74, v3
	v_cndmask_b32_e64 v74, v2, v74, s[40:41]
	s_waitcnt lgkmcnt(14)
	v_mul_f32_e32 v3, s5, v103
	v_mul_f32_e32 v75, s4, v75
	v_add_f32_e32 v75, v75, v3
	v_cndmask_b32_e64 v75, v2, v75, s[42:43]
	s_waitcnt lgkmcnt(13)
	v_mul_f32_e32 v3, s5, v104
	v_mul_f32_e32 v76, s4, v76
	v_add_f32_e32 v76, v76, v3
	v_cndmask_b32_e64 v76, v2, v76, s[44:45]
	s_waitcnt lgkmcnt(12)
	v_mul_f32_e32 v3, s5, v105
	v_mul_f32_e32 v77, s4, v77
	v_add_f32_e32 v77, v77, v3
	v_cndmask_b32_e64 v77, v2, v77, s[46:47]
	s_waitcnt lgkmcnt(11)
	v_mul_f32_e32 v3, s5, v106
	v_mul_f32_e32 v68, s4, v68
	v_add_f32_e32 v68, v68, v3
	v_cndmask_b32_e64 v68, v2, v68, s[28:29]
	s_waitcnt lgkmcnt(10)
	v_mul_f32_e32 v3, s5, v107
	v_mul_f32_e32 v69, s4, v69
	v_add_f32_e32 v69, v69, v3
	v_cndmask_b32_e64 v69, v2, v69, s[30:31]
	s_waitcnt lgkmcnt(9)
	v_mul_f32_e32 v3, s5, v108
	v_mul_f32_e32 v70, s4, v70
	v_add_f32_e32 v70, v70, v3
	v_cndmask_b32_e64 v70, v2, v70, s[34:35]
	s_waitcnt lgkmcnt(8)
	v_mul_f32_e32 v3, s5, v109
	v_mul_f32_e32 v71, s4, v71
	v_add_f32_e32 v71, v71, v3
	v_cndmask_b32_e64 v71, v2, v71, s[88:89]
	s_waitcnt lgkmcnt(7)
	v_mul_f32_e32 v3, s5, v110
	v_mul_f32_e32 v64, s4, v64
	v_add_f32_e32 v64, v64, v3
	v_cndmask_b32_e64 v64, v2, v64, s[12:13]
	s_waitcnt lgkmcnt(6)
	v_mul_f32_e32 v3, s5, v111
	v_mul_f32_e32 v65, s4, v65
	v_add_f32_e32 v65, v65, v3
	v_cndmask_b32_e64 v65, v2, v65, s[14:15]
	s_waitcnt lgkmcnt(5)
	v_mul_f32_e32 v3, s5, v112
	v_mul_f32_e32 v66, s4, v66
	v_add_f32_e32 v66, v66, v3
	v_cndmask_b32_e64 v66, v2, v66, s[60:61]
	s_waitcnt lgkmcnt(4)
	v_mul_f32_e32 v3, s5, v113
	v_mul_f32_e32 v67, s4, v67
	v_add_f32_e32 v67, v67, v3
	v_cndmask_b32_e64 v67, v2, v67, s[6:7]
	s_waitcnt lgkmcnt(3)
	v_mul_f32_e32 v3, s5, v114
	v_mul_f32_e32 v60, s4, v60
	v_add_f32_e32 v60, v60, v3
	v_cndmask_b32_e64 v60, v2, v60, s[48:49]
	s_waitcnt lgkmcnt(2)
	v_mul_f32_e32 v3, s5, v115
	v_mul_f32_e32 v61, s4, v61
	v_add_f32_e32 v61, v61, v3
	v_cndmask_b32_e64 v61, v2, v61, s[50:51]
	s_waitcnt lgkmcnt(1)
	v_mul_f32_e32 v3, s5, v210
	v_mul_f32_e32 v62, s4, v62
	v_add_f32_e32 v62, v62, v3
	v_cndmask_b32_e64 v62, v2, v62, s[52:53]
	s_waitcnt lgkmcnt(0)
	v_mul_f32_e32 v3, s5, v211
	v_mul_f32_e32 v63, s4, v63
	v_add_f32_e32 v63, v63, v3
	v_cndmask_b32_e64 v63, v2, v63, s[54:55]
